# v25: v22 plus nt loads for the combine phases' residual rows
# baseline (speedup 1.0000x reference)
.LBB0_813:
	s_or_b64 exec, exec, s[8:9]
	s_waitcnt lgkmcnt(0)
	s_barrier
	s_load_dwordx8 s[12:19], s[84:85], 0xd8
	s_load_dwordx4 s[4:7], s[84:85], 0xf8
	s_load_dwordx2 s[20:21], s[84:85], 0x108
	s_add_i32 s8, s33, s68
	s_ashr_i32 s69, s68, 31
	s_ashr_i32 s9, s8, 31
	s_mov_b32 s0, s8
	s_lshl_b64 s[24:25], s[68:69], 11
	v_writelane_b32 v253, s0, 34
	s_lshl_b64 s[26:27], s[8:9], 11
	v_mov_b32_e32 v39, v0
	s_waitcnt lgkmcnt(0)
	s_mov_b32 s8, s21
	v_writelane_b32 v253, s1, 35
	s_mov_b32 s0, s7
	v_and_b32_e32 v74, 63, v39
	s_add_u32 s22, s20, 0x3e00000
	s_addc_u32 s23, s8, 0
	v_lshlrev_b32_e32 v34, 4, v74
	v_mov_b32_e32 v35, 0
	v_lshl_add_u64 v[2:3], s[18:19], 0, v[34:35]
	s_mov_b64 s[0:1], 0x1000
	v_lshl_add_u64 v[6:7], s[4:5], 0, v[34:35]
	s_add_u32 s18, s20, 0x3900000
	v_lshl_add_u64 v[26:27], v[2:3], 0, s[0:1]
	v_lshl_add_u64 v[30:31], v[6:7], 0, s[0:1]
	s_movk_i32 s0, 0x1000
	s_addc_u32 s19, s8, 0
	v_add_co_u32_e32 v2, vcc, s0, v2
	s_add_u32 s10, s20, 0xa100000
	s_nop 0
	v_addc_co_u32_e32 v3, vcc, 0, v3, vcc
	s_addc_u32 s11, s8, 0
	v_add_co_u32_e32 v6, vcc, s0, v6
	s_add_u32 s0, s10, s24
	v_writelane_b32 v253, s24, 36
	s_addc_u32 s1, s11, s25
	s_add_u32 s4, s10, s26
	v_writelane_b32 v253, s25, 37
	v_lshlrev_b32_e32 v34, 3, v74
	v_addc_co_u32_e32 v7, vcc, 0, v7, vcc
	v_writelane_b32 v253, s26, 38
	s_addc_u32 s5, s11, s27
	v_lshl_add_u64 v[36:37], s[0:1], 0, v[34:35]
	global_load_dwordx4 v[2:5], v[2:3], off nt
	s_nop 0
	global_load_dwordx4 v[6:9], v[6:7], off nt
	s_nop 0
	global_load_dwordx4 v[10:13], v[26:27], off offset:1024
	global_load_dwordx4 v[14:17], v[26:27], off offset:2048
	global_load_dwordx4 v[18:21], v[30:31], off offset:1024
	global_load_dwordx4 v[22:25], v[30:31], off offset:2048
	s_nop 0
	global_load_dwordx4 v[26:29], v[26:27], off offset:3072
	s_nop 0
	global_load_dwordx4 v[30:33], v[30:31], off offset:3072
	v_lshl_add_u64 v[46:47], s[4:5], 0, v[34:35]
	global_load_dwordx2 v[64:65], v[36:37], off nt
	global_load_dwordx2 v[62:63], v[36:37], off offset:512 nt
	global_load_dwordx2 v[60:61], v[36:37], off offset:1024 nt
	global_load_dwordx2 v[58:59], v[36:37], off offset:1536 nt
	global_load_dwordx2 v[44:45], v[46:47], off nt
	global_load_dwordx2 v[42:43], v[46:47], off offset:512 nt
	global_load_dwordx2 v[40:41], v[46:47], off offset:1024 nt
	s_nop 0
	global_load_dwordx2 v[36:37], v[46:47], off offset:1536 nt
	s_mov_b32 s7, s8
	v_cmp_gt_u32_e64 s[8:9], 16, v74
	v_mov_b32_e32 v75, -1
	v_lshlrev_b32_e32 v38, 11, v74
	v_mov_b32_e32 v82, v35
	v_mov_b32_e32 v81, -1
	v_writelane_b32 v253, s27, 39
	s_and_saveexec_b64 s[24:25], s[8:9]
	s_cbranch_execz .LBB0_815
	v_readlane_b32 s0, v253, 34
	v_readlane_b32 s1, v253, 35
	s_mov_b32 s4, s0
	s_ashr_i32 s0, s0, 11
	s_ashr_i32 s1, s0, 31
	s_lshl_b64 s[0:1], s[0:1], 15
	s_and_b32 s4, s4, 0x7ff
	s_or_b32 s0, s0, s4
	s_ashr_i32 s4, s68, 11
	s_ashr_i32 s5, s4, 31
	s_lshl_b64 s[4:5], s[4:5], 15
	s_and_b32 s6, s68, 0x7ff
	s_or_b32 s4, s4, s6
	v_or_b32_e32 v46, s4, v38
	v_mov_b32_e32 v47, s5
	v_lshl_add_u64 v[48:49], v[46:47], 1, s[22:23]
	v_lshl_add_u64 v[46:47], v[46:47], 2, s[18:19]
	global_load_sshort v81, v[48:49], off
	global_load_dword v82, v[46:47], off
	v_or_b32_e32 v46, s0, v38
	v_mov_b32_e32 v47, s1
	v_lshl_add_u64 v[48:49], v[46:47], 1, s[22:23]
	v_lshl_add_u64 v[46:47], v[46:47], 2, s[18:19]
	global_load_sshort v75, v[48:49], off
	global_load_dword v35, v[46:47], off

.LBB0_818:
	s_add_i32 s26, s28, s94
	s_cmp_gt_i32 s26, 0xffff
	v_mov_b32_e32 v80, v35
	s_cbranch_scc1 .LBB0_822
	s_ashr_i32 s27, s26, 31
	s_lshl_b64 s[0:1], s[26:27], 11
	v_lshl_add_u64 v[50:51], v[48:49], 0, s[0:1]
	global_load_dwordx2 v[56:57], v[50:51], off nt
	global_load_dwordx2 v[54:55], v[50:51], off offset:512 nt
	global_load_dwordx2 v[52:53], v[50:51], off offset:1024 nt
	s_nop 0
	global_load_dwordx2 v[50:51], v[50:51], off offset:1536 nt
	v_mov_b32_e32 v79, v75
	v_mov_b32_e32 v80, v35
	s_and_saveexec_b64 s[10:11], s[8:9]
	s_cbranch_execz .LBB0_821
	s_ashr_i32 s0, s26, 11
	s_ashr_i32 s1, s0, 31
	s_lshl_b64 s[0:1], s[0:1], 15
	v_or_b32_e32 v34, s0, v38
	s_and_b32 s0, s26, 0x7ff
	v_mov_b32_e32 v67, s1
	v_or_b32_e32 v66, s0, v34
	v_lshl_add_u64 v[68:69], v[66:67], 1, s[22:23]
	v_lshl_add_u64 v[66:67], v[66:67], 2, s[18:19]
	global_load_sshort v79, v[68:69], off
	global_load_dword v80, v[66:67], off

.LBB0_1427:
	s_or_b64 exec, exec, s[8:9]
	s_waitcnt lgkmcnt(0)
	s_barrier
	s_load_dwordx4 s[4:7], s[84:85], 0xf8
	s_load_dwordx2 s[24:25], s[84:85], 0x108
	s_load_dwordx8 s[16:23], s[84:85], 0xd8
	v_mov_b32_e32 v39, v0
	s_waitcnt lgkmcnt(0)
	s_mov_b32 s0, s7
	v_and_b32_e32 v74, 63, v39
	s_mov_b32 s8, s25
	s_add_u32 s26, s24, 0x3e00000
	v_lshlrev_b32_e32 v34, 4, v74
	v_mov_b32_e32 v35, 0
	s_addc_u32 s27, s8, 0
	v_lshl_add_u64 v[2:3], s[22:23], 0, v[34:35]
	s_mov_b64 s[0:1], 0x3000
	v_lshl_add_u64 v[6:7], s[4:5], 0, v[34:35]
	v_lshl_add_u64 v[26:27], v[2:3], 0, s[0:1]
	v_lshl_add_u64 v[30:31], v[6:7], 0, s[0:1]
	s_movk_i32 s0, 0x3000
	s_add_u32 s22, s24, 0x3900000
	v_add_co_u32_e32 v2, vcc, s0, v2
	s_addc_u32 s23, s8, 0
	s_nop 0
	v_addc_co_u32_e32 v3, vcc, 0, v3, vcc
	s_add_u32 s14, s24, 0xa100000
	v_add_co_u32_e32 v6, vcc, s0, v6
	s_addc_u32 s15, s8, 0
	v_readlane_b32 s0, v253, 36
	v_readlane_b32 s1, v253, 37
	s_add_u32 s0, s14, s0
	s_addc_u32 s1, s15, s1
	v_readlane_b32 s4, v253, 38
	v_readlane_b32 s5, v253, 39
	s_add_u32 s4, s14, s4
	v_lshlrev_b32_e32 v34, 3, v74
	v_addc_co_u32_e32 v7, vcc, 0, v7, vcc
	s_addc_u32 s5, s15, s5
	v_lshl_add_u64 v[36:37], s[0:1], 0, v[34:35]
	global_load_dwordx4 v[2:5], v[2:3], off nt
	s_nop 0
	global_load_dwordx4 v[6:9], v[6:7], off nt
	s_nop 0
	global_load_dwordx4 v[10:13], v[26:27], off offset:1024
	global_load_dwordx4 v[14:17], v[26:27], off offset:2048
	global_load_dwordx4 v[18:21], v[30:31], off offset:1024
	global_load_dwordx4 v[22:25], v[30:31], off offset:2048
	s_nop 0
	global_load_dwordx4 v[26:29], v[26:27], off offset:3072
	s_nop 0
	global_load_dwordx4 v[30:33], v[30:31], off offset:3072
	v_lshl_add_u64 v[46:47], s[4:5], 0, v[34:35]
	global_load_dwordx2 v[64:65], v[36:37], off nt
	global_load_dwordx2 v[62:63], v[36:37], off offset:512 nt
	global_load_dwordx2 v[60:61], v[36:37], off offset:1024 nt
	global_load_dwordx2 v[58:59], v[36:37], off offset:1536 nt
	global_load_dwordx2 v[44:45], v[46:47], off nt
	global_load_dwordx2 v[42:43], v[46:47], off offset:512 nt
	global_load_dwordx2 v[40:41], v[46:47], off offset:1024 nt
	s_nop 0
	global_load_dwordx2 v[36:37], v[46:47], off offset:1536 nt
	s_mov_b32 s7, s8
	v_cmp_gt_u32_e64 s[12:13], 16, v74
	v_mov_b32_e32 v75, -1
	v_lshlrev_b32_e32 v38, 11, v74
	v_mov_b32_e32 v82, v35
	v_mov_b32_e32 v81, -1
	s_and_saveexec_b64 s[8:9], s[12:13]
	s_cbranch_execz .LBB0_1429
	v_readlane_b32 s0, v253, 34
	v_readlane_b32 s1, v253, 35
	s_mov_b32 s4, s0
	s_ashr_i32 s0, s0, 11
	s_ashr_i32 s1, s0, 31
	s_lshl_b64 s[0:1], s[0:1], 15
	s_and_b32 s4, s4, 0x7ff
	s_or_b32 s0, s0, s4
	s_ashr_i32 s4, s68, 11
	s_ashr_i32 s5, s4, 31
	s_lshl_b64 s[4:5], s[4:5], 15
	s_and_b32 s6, s68, 0x7ff
	s_or_b32 s4, s4, s6
	v_or_b32_e32 v46, s4, v38
	v_mov_b32_e32 v47, s5
	v_lshl_add_u64 v[48:49], v[46:47], 1, s[26:27]
	v_lshl_add_u64 v[46:47], v[46:47], 2, s[22:23]
	global_load_sshort v81, v[48:49], off
	global_load_dword v82, v[46:47], off
	v_or_b32_e32 v46, s0, v38
	v_mov_b32_e32 v47, s1
	v_lshl_add_u64 v[48:49], v[46:47], 1, s[26:27]
	v_lshl_add_u64 v[46:47], v[46:47], 2, s[22:23]
	global_load_sshort v75, v[48:49], off
	global_load_dword v35, v[46:47], off

.LBB0_1432:
	s_add_i32 s30, s34, s94
	s_cmp_gt_i32 s30, 0xffff
	v_mov_b32_e32 v80, v35
	s_cbranch_scc1 .LBB0_1436
	s_ashr_i32 s31, s30, 31
	s_lshl_b64 s[0:1], s[30:31], 11
	v_lshl_add_u64 v[50:51], v[48:49], 0, s[0:1]
	global_load_dwordx2 v[56:57], v[50:51], off nt
	global_load_dwordx2 v[54:55], v[50:51], off offset:512 nt
	global_load_dwordx2 v[52:53], v[50:51], off offset:1024 nt
	s_nop 0
	global_load_dwordx2 v[50:51], v[50:51], off offset:1536 nt
	v_mov_b32_e32 v79, v75
	v_mov_b32_e32 v80, v35
	s_and_saveexec_b64 s[14:15], s[12:13]
	s_cbranch_execz .LBB0_1435
	s_ashr_i32 s0, s30, 11
	s_ashr_i32 s1, s0, 31
	s_lshl_b64 s[0:1], s[0:1], 15
	v_or_b32_e32 v34, s0, v38
	s_and_b32 s0, s30, 0x7ff
	v_mov_b32_e32 v67, s1
	v_or_b32_e32 v66, s0, v34
	v_lshl_add_u64 v[68:69], v[66:67], 1, s[26:27]
	v_lshl_add_u64 v[66:67], v[66:67], 2, s[22:23]
	global_load_sshort v79, v[68:69], off
	global_load_dword v80, v[66:67], off

.LBB0_2166:
	s_or_b64 exec, exec, s[12:13]
	s_waitcnt lgkmcnt(0)
	s_barrier
	s_load_dwordx8 s[16:23], s[84:85], 0xd8
	s_load_dwordx4 s[8:11], s[84:85], 0xf8
	s_load_dwordx2 s[0:1], s[84:85], 0x108
	v_mov_b32_e32 v45, v0
	v_mov_b32_e32 v35, 0
	v_and_b32_e32 v74, 63, v45
	s_waitcnt lgkmcnt(0)
	s_mov_b32 s6, s0
	s_mov_b32 s0, s10
	s_add_u32 s24, s6, 0x3e00000
	s_addc_u32 s25, s1, 0
	v_lshlrev_b32_e32 v34, 4, v74
	v_lshl_add_u64 v[2:3], s[22:23], 0, v[34:35]
	s_mov_b64 s[4:5], 0x5000
	s_movk_i32 s0, 0x5000
	s_add_u32 s22, s6, 0x3900000
	v_lshl_add_u64 v[26:27], v[2:3], 0, s[4:5]
	v_add_co_u32_e32 v2, vcc, s0, v2
	s_addc_u32 s23, s1, 0
	v_lshl_add_u64 v[6:7], s[8:9], 0, v[34:35]
	v_addc_co_u32_e32 v3, vcc, 0, v3, vcc
	s_add_u32 s14, s6, 0xa100000
	s_mov_b32 s7, s1
	v_lshl_add_u64 v[30:31], v[6:7], 0, s[4:5]
	v_add_co_u32_e32 v6, vcc, s0, v6
	s_addc_u32 s15, s1, 0
	v_readlane_b32 s0, v253, 36
	v_readlane_b32 s1, v253, 37
	s_add_u32 s0, s14, s0
	s_addc_u32 s1, s15, s1
	v_readlane_b32 s4, v253, 38
	v_readlane_b32 s5, v253, 39
	s_add_u32 s4, s14, s4
	s_addc_u32 s5, s15, s5
	v_lshlrev_b32_e32 v34, 3, v74
	v_addc_co_u32_e32 v7, vcc, 0, v7, vcc
	v_lshl_add_u64 v[42:43], s[0:1], 0, v[34:35]
	v_lshl_add_u64 v[46:47], s[4:5], 0, v[34:35]
	global_load_dwordx4 v[2:5], v[2:3], off nt
	s_nop 0
	global_load_dwordx4 v[6:9], v[6:7], off nt
	s_nop 0
	global_load_dwordx4 v[10:13], v[26:27], off offset:1024
	global_load_dwordx4 v[14:17], v[30:31], off offset:1024
	global_load_dwordx4 v[18:21], v[26:27], off offset:2048
	global_load_dwordx4 v[22:25], v[30:31], off offset:2048
	s_nop 0
	global_load_dwordx4 v[26:29], v[26:27], off offset:3072
	s_nop 0
	global_load_dwordx4 v[30:33], v[30:31], off offset:3072
	v_cmp_gt_u32_e64 s[12:13], 16, v74
	global_load_dwordx2 v[62:63], v[42:43], off nt
	global_load_dwordx2 v[36:37], v[46:47], off nt
	global_load_dwordx2 v[64:65], v[42:43], off offset:512 nt
	global_load_dwordx2 v[38:39], v[46:47], off offset:512 nt
	global_load_dwordx2 v[60:61], v[42:43], off offset:1024 nt
	global_load_dwordx2 v[40:41], v[46:47], off offset:1024 nt
	global_load_dwordx2 v[58:59], v[42:43], off offset:1536 nt
	s_nop 0
	global_load_dwordx2 v[42:43], v[46:47], off offset:1536 nt
	v_mov_b32_e32 v75, -1
	v_lshlrev_b32_e32 v44, 11, v74
	v_mov_b32_e32 v82, v35
	v_mov_b32_e32 v81, -1
	s_and_saveexec_b64 s[26:27], s[12:13]
	s_cbranch_execz .LBB0_2168
	v_readlane_b32 s0, v253, 34
	v_readlane_b32 s1, v253, 35
	s_mov_b32 s4, s0
	s_ashr_i32 s0, s0, 11
	s_ashr_i32 s1, s0, 31
	s_lshl_b64 s[0:1], s[0:1], 15
	s_and_b32 s4, s4, 0x7ff
	s_or_b32 s0, s0, s4
	s_ashr_i32 s4, s68, 11
	s_ashr_i32 s5, s4, 31
	s_lshl_b64 s[4:5], s[4:5], 15
	s_and_b32 s8, s68, 0x7ff
	s_or_b32 s4, s4, s8
	v_or_b32_e32 v46, s4, v44
	v_mov_b32_e32 v47, s5
	v_lshl_add_u64 v[48:49], v[46:47], 1, s[24:25]
	v_lshl_add_u64 v[46:47], v[46:47], 2, s[22:23]
	global_load_sshort v81, v[48:49], off
	global_load_dword v82, v[46:47], off
	v_or_b32_e32 v46, s0, v44
	v_mov_b32_e32 v47, s1
	v_lshl_add_u64 v[48:49], v[46:47], 1, s[24:25]
	v_lshl_add_u64 v[46:47], v[46:47], 2, s[22:23]
	global_load_sshort v75, v[48:49], off
	global_load_dword v35, v[46:47], off

.LBB0_2171:
	s_add_i32 s28, s30, s94
	s_cmp_gt_i32 s28, 0xffff
	v_mov_b32_e32 v80, v35
	s_cbranch_scc1 .LBB0_2175
	s_ashr_i32 s29, s28, 31
	s_lshl_b64 s[0:1], s[28:29], 11
	v_lshl_add_u64 v[50:51], v[48:49], 0, s[0:1]
	global_load_dwordx2 v[56:57], v[50:51], off nt
	global_load_dwordx2 v[54:55], v[50:51], off offset:512 nt
	global_load_dwordx2 v[52:53], v[50:51], off offset:1024 nt
	s_nop 0
	global_load_dwordx2 v[50:51], v[50:51], off offset:1536 nt
	v_mov_b32_e32 v79, v75
	v_mov_b32_e32 v80, v35
	s_and_saveexec_b64 s[14:15], s[12:13]
	s_cbranch_execz .LBB0_2174
	s_ashr_i32 s0, s28, 11
	s_ashr_i32 s1, s0, 31
	s_lshl_b64 s[0:1], s[0:1], 15
	v_or_b32_e32 v34, s0, v44
	s_and_b32 s0, s28, 0x7ff
	v_mov_b32_e32 v67, s1
	v_or_b32_e32 v66, s0, v34
	v_lshl_add_u64 v[68:69], v[66:67], 1, s[24:25]
	v_lshl_add_u64 v[66:67], v[66:67], 2, s[22:23]
	global_load_sshort v79, v[68:69], off
	global_load_dword v80, v[66:67], off

.LBB0_2874:
	s_or_b64 exec, exec, s[2:3]
	s_waitcnt lgkmcnt(0)
	s_barrier
	s_load_dwordx8 s[12:19], s[84:85], 0xf0
	v_mov_b32_e32 v33, 0
	v_and_b32_e32 v44, 63, v0
	v_lshlrev_b32_e32 v32, 4, v44
	s_waitcnt lgkmcnt(0)
	s_mov_b32 s8, s18
	s_add_u32 s4, s8, 0x3e00000
	s_addc_u32 s5, s19, 0
	v_lshl_add_u64 v[0:1], s[12:13], 0, v[32:33]
	s_mov_b64 s[0:1], 0x7000
	v_lshl_add_u64 v[4:5], s[14:15], 0, v[32:33]
	v_lshl_add_u64 v[34:35], v[0:1], 0, s[0:1]
	v_lshl_add_u64 v[36:37], v[4:5], 0, s[0:1]
	s_movk_i32 s0, 0x7000
	s_add_u32 s6, s8, 0x3900000
	v_add_co_u32_e32 v0, vcc, s0, v0
	s_addc_u32 s7, s19, 0
	s_nop 0
	v_addc_co_u32_e32 v1, vcc, 0, v1, vcc
	s_add_u32 s10, s8, 0xa100000
	v_add_co_u32_e32 v38, vcc, s0, v4
	s_addc_u32 s11, s19, 0
	v_readlane_b32 s0, v253, 36
	v_readlane_b32 s1, v253, 37
	s_add_u32 s0, s10, s0
	s_addc_u32 s1, s11, s1
	v_readlane_b32 s12, v253, 38
	s_mov_b32 s2, s16
	v_addc_co_u32_e32 v39, vcc, 0, v5, vcc
	v_readlane_b32 s13, v253, 39
	s_add_u32 s12, s10, s12
	v_lshlrev_b32_e32 v32, 3, v44
	global_load_dwordx4 v[0:3], v[0:1], off
	s_nop 0
	global_load_dwordx4 v[4:7], v[38:39], off
	global_load_dwordx4 v[8:11], v[34:35], off offset:1024
	global_load_dwordx4 v[12:15], v[34:35], off offset:2048
	global_load_dwordx4 v[16:19], v[36:37], off offset:1024
	global_load_dwordx4 v[20:23], v[36:37], off offset:2048
	global_load_dwordx4 v[24:27], v[34:35], off offset:3072
	global_load_dwordx4 v[28:31], v[36:37], off offset:3072
	s_addc_u32 s13, s11, s13
	v_lshl_add_u64 v[38:39], s[0:1], 0, v[32:33]
	v_lshl_add_u64 v[46:47], s[12:13], 0, v[32:33]
	global_load_dwordx2 v[64:65], v[38:39], off nt
	global_load_dwordx2 v[62:63], v[38:39], off offset:512 nt
	global_load_dwordx2 v[60:61], v[38:39], off offset:1024 nt
	global_load_dwordx2 v[58:59], v[38:39], off offset:1536 nt
	global_load_dwordx2 v[42:43], v[46:47], off nt
	global_load_dwordx2 v[40:41], v[46:47], off offset:512 nt
	global_load_dwordx2 v[36:37], v[46:47], off offset:1024 nt
	global_load_dwordx2 v[34:35], v[46:47], off offset:1536 nt
	s_mov_b32 s14, s19
	v_cmp_gt_u32_e64 s[0:1], 16, v44
	v_mov_b32_e32 v39, -1
	v_lshlrev_b32_e32 v38, 11, v44
	v_mov_b32_e32 v80, v33
	v_mov_b32_e32 v79, -1
	s_and_saveexec_b64 s[12:13], s[0:1]
	s_cbranch_execz .LBB0_2876
	v_readlane_b32 s18, v253, 34
	s_ashr_i32 s20, s68, 11
	v_readlane_b32 s19, v253, 35
	s_mov_b32 s16, s18
	s_ashr_i32 s18, s18, 11
	s_ashr_i32 s21, s20, 31
	s_ashr_i32 s19, s18, 31
	s_lshl_b64 s[20:21], s[20:21], 15
	s_and_b32 s9, s68, 0x7ff
	s_lshl_b64 s[18:19], s[18:19], 15
	s_and_b32 s3, s16, 0x7ff
	s_or_b32 s9, s20, s9
	s_or_b32 s3, s18, s3
	v_or_b32_e32 v46, s9, v38
	v_mov_b32_e32 v47, s21
	v_lshl_add_u64 v[48:49], v[46:47], 1, s[4:5]
	v_or_b32_e32 v50, s3, v38
	v_mov_b32_e32 v51, s19
	v_lshl_add_u64 v[46:47], v[46:47], 2, s[6:7]
	v_lshl_add_u64 v[52:53], v[50:51], 1, s[4:5]
	v_lshl_add_u64 v[50:51], v[50:51], 2, s[6:7]
	global_load_sshort v79, v[48:49], off
	global_load_dword v80, v[46:47], off
	global_load_sshort v39, v[52:53], off
	global_load_dword v33, v[50:51], off

.LBB0_2879:
	s_add_i32 s10, s68, s94
	s_cmp_gt_i32 s10, 0xffff
	v_mov_b32_e32 v78, v33
	s_cbranch_scc1 .LBB0_2883
	s_ashr_i32 s11, s10, 31
	s_lshl_b64 s[2:3], s[10:11], 11
	v_lshl_add_u64 v[66:67], v[46:47], 0, s[2:3]
	global_load_dwordx2 v[56:57], v[66:67], off nt
	global_load_dwordx2 v[54:55], v[66:67], off offset:512 nt
	global_load_dwordx2 v[52:53], v[66:67], off offset:1024 nt
	global_load_dwordx2 v[50:51], v[66:67], off offset:1536 nt
	v_mov_b32_e32 v77, v39
	v_mov_b32_e32 v78, v33
	s_and_saveexec_b64 s[2:3], s[0:1]
	s_cbranch_execz .LBB0_2882
	s_ashr_i32 s12, s10, 11
	s_ashr_i32 s13, s12, 31
	s_lshl_b64 s[12:13], s[12:13], 15
	v_or_b32_e32 v32, s12, v38
	s_and_b32 s11, s10, 0x7ff
	v_mov_b32_e32 v67, s13
	v_or_b32_e32 v66, s11, v32
	v_lshl_add_u64 v[68:69], v[66:67], 1, s[4:5]
	v_lshl_add_u64 v[66:67], v[66:67], 2, s[6:7]
	global_load_sshort v77, v[68:69], off
	global_load_dword v78, v[66:67], off
